# GEMM accumulator zeroing between units uses 64 v_mov_b64 instead of 128 v_mov_b32
# speedup vs baseline: 1.0037x; 1.0037x over previous
; template <class Epi, class Sched, bool ALIGN_EPI = false, bool SP2 = false>
; __device__ __forceinline__ void gemm_phase(PG8_LAS unsigned char* lds, const Gemm g, const Sched& S, const Epi& E) {
;     ...
; #pragma unroll
;         for (int a = 0; a < 2; ++a)
; #pragma unroll
;             for (int b = 0; b < 2; ++b)
; #pragma unroll
;                 for (int m = 0; m < 4; ++m)
; #pragma unroll
;                     for (int n = 0; n < 2; ++n) acc[a][b][m][n] = (f32x4){0.f, 0.f, 0.f, 0.f};
;         cur = nxt; cA = nA; cB = nB; ++ui;
.LBB0_388:
	s_add_i32 s28, s50, -2
	s_add_u32 s18, s18, 0x80
	s_addc_u32 s19, s19, 0
	s_add_u32 s29, s12, 0x100
	s_addc_u32 s43, s13, 0
	s_mov_b32 s12, 0
	v_mov_b64_e32 v[2:3], 0
	v_mov_b64_e32 v[4:5], 0
	v_mov_b64_e32 v[6:7], 0
	v_mov_b64_e32 v[8:9], 0
	v_mov_b64_e32 v[10:11], 0
	v_mov_b64_e32 v[12:13], 0
	v_mov_b64_e32 v[14:15], 0
	v_mov_b64_e32 v[16:17], 0
	v_mov_b64_e32 v[18:19], 0
	v_mov_b64_e32 v[20:21], 0
	v_mov_b64_e32 v[22:23], 0
	v_mov_b64_e32 v[24:25], 0
	v_mov_b64_e32 v[26:27], 0
	v_mov_b64_e32 v[28:29], 0
	v_mov_b64_e32 v[30:31], 0
	v_mov_b64_e32 v[32:33], 0
	v_mov_b64_e32 v[34:35], 0
	v_mov_b64_e32 v[36:37], 0
	v_mov_b64_e32 v[38:39], 0
	v_mov_b64_e32 v[40:41], 0
	v_mov_b64_e32 v[42:43], 0
	v_mov_b64_e32 v[44:45], 0
	v_mov_b64_e32 v[46:47], 0
	v_mov_b64_e32 v[48:49], 0
	v_mov_b64_e32 v[50:51], 0
	v_mov_b64_e32 v[52:53], 0
	v_mov_b64_e32 v[54:55], 0
	v_mov_b64_e32 v[56:57], 0
	v_mov_b64_e32 v[58:59], 0
	v_mov_b64_e32 v[60:61], 0
	v_mov_b64_e32 v[62:63], 0
	v_mov_b64_e32 v[64:65], 0
	v_mov_b64_e32 v[66:67], 0
	v_mov_b64_e32 v[68:69], 0
	v_mov_b64_e32 v[70:71], 0
	v_mov_b64_e32 v[72:73], 0
	v_mov_b64_e32 v[74:75], 0
	v_mov_b64_e32 v[76:77], 0
	v_mov_b64_e32 v[78:79], 0
	v_mov_b64_e32 v[80:81], 0
	v_mov_b64_e32 v[82:83], 0
	v_mov_b64_e32 v[84:85], 0
	v_mov_b64_e32 v[86:87], 0
	v_mov_b64_e32 v[88:89], 0
	v_mov_b64_e32 v[90:91], 0
	v_mov_b64_e32 v[92:93], 0
	v_mov_b64_e32 v[94:95], 0
	v_mov_b64_e32 v[96:97], 0
	v_mov_b64_e32 v[98:99], 0
	v_mov_b64_e32 v[100:101], 0
	v_mov_b64_e32 v[102:103], 0
	v_mov_b64_e32 v[104:105], 0
	v_mov_b64_e32 v[106:107], 0
	v_mov_b64_e32 v[108:109], 0
	v_mov_b64_e32 v[110:111], 0
	v_mov_b64_e32 v[112:113], 0
	v_mov_b64_e32 v[114:115], 0
	v_mov_b64_e32 v[116:117], 0
	v_mov_b64_e32 v[118:119], 0
	v_mov_b64_e32 v[120:121], 0
	v_mov_b64_e32 v[122:123], 0
	v_mov_b64_e32 v[124:125], 0
	v_mov_b64_e32 v[126:127], 0
	v_mov_b64_e32 v[128:129], 0

; #define PG8_BAR __builtin_amdgcn_s_barrier()
; template <class Epi, class Sched, bool ALIGN_EPI = false, bool SP2 = false>
; __device__ __forceinline__ void gemm_phase(PG8_LAS unsigned char* lds, const Gemm g, const Sched& S, const Epi& E) {
;     ...
; #pragma unroll
;         for (int a = 0; a < 2; ++a)
; #pragma unroll
;             for (int b = 0; b < 2; ++b)
; #pragma unroll
;                 for (int m = 0; m < 4; ++m)
; #pragma unroll
;                     for (int n = 0; n < 2; ++n) acc[a][b][m][n] = (f32x4){0.f, 0.f, 0.f, 0.f};
;         cur = nxt; cA = nA; cB = nB; ++ui;
;         if constexpr (ALIGN_EPI) { if (wr == 1) PG8_BAR; }
.LBB0_397:
	s_and_b64 vcc, exec, s[40:41]
	v_mov_b64_e32 v[2:3], 0
	v_mov_b64_e32 v[4:5], 0
	v_mov_b64_e32 v[6:7], 0
	v_mov_b64_e32 v[8:9], 0
	v_mov_b64_e32 v[10:11], 0
	v_mov_b64_e32 v[12:13], 0
	v_mov_b64_e32 v[14:15], 0
	v_mov_b64_e32 v[16:17], 0
	v_mov_b64_e32 v[18:19], 0
	v_mov_b64_e32 v[20:21], 0
	v_mov_b64_e32 v[22:23], 0
	v_mov_b64_e32 v[24:25], 0
	v_mov_b64_e32 v[26:27], 0
	v_mov_b64_e32 v[28:29], 0
	v_mov_b64_e32 v[30:31], 0
	v_mov_b64_e32 v[32:33], 0
	v_mov_b64_e32 v[34:35], 0
	v_mov_b64_e32 v[36:37], 0
	v_mov_b64_e32 v[38:39], 0
	v_mov_b64_e32 v[40:41], 0
	v_mov_b64_e32 v[42:43], 0
	v_mov_b64_e32 v[44:45], 0
	v_mov_b64_e32 v[46:47], 0
	v_mov_b64_e32 v[48:49], 0
	v_mov_b64_e32 v[50:51], 0
	v_mov_b64_e32 v[52:53], 0
	v_mov_b64_e32 v[54:55], 0
	v_mov_b64_e32 v[56:57], 0
	v_mov_b64_e32 v[58:59], 0
	v_mov_b64_e32 v[60:61], 0
	v_mov_b64_e32 v[62:63], 0
	v_mov_b64_e32 v[64:65], 0
	v_mov_b64_e32 v[66:67], 0
	v_mov_b64_e32 v[68:69], 0
	v_mov_b64_e32 v[70:71], 0
	v_mov_b64_e32 v[72:73], 0
	v_mov_b64_e32 v[74:75], 0
	v_mov_b64_e32 v[76:77], 0
	v_mov_b64_e32 v[78:79], 0
	v_mov_b64_e32 v[80:81], 0
	v_mov_b64_e32 v[82:83], 0
	v_mov_b64_e32 v[84:85], 0
	v_mov_b64_e32 v[86:87], 0
	v_mov_b64_e32 v[88:89], 0
	v_mov_b64_e32 v[90:91], 0
	v_mov_b64_e32 v[92:93], 0
	v_mov_b64_e32 v[94:95], 0
	v_mov_b64_e32 v[96:97], 0
	v_mov_b64_e32 v[98:99], 0
	v_mov_b64_e32 v[100:101], 0
	v_mov_b64_e32 v[102:103], 0
	v_mov_b64_e32 v[104:105], 0
	v_mov_b64_e32 v[106:107], 0
	v_mov_b64_e32 v[108:109], 0
	v_mov_b64_e32 v[110:111], 0
	v_mov_b64_e32 v[112:113], 0
	v_mov_b64_e32 v[114:115], 0
	v_mov_b64_e32 v[116:117], 0
	v_mov_b64_e32 v[118:119], 0
	v_mov_b64_e32 v[120:121], 0
	v_mov_b64_e32 v[122:123], 0
	v_mov_b64_e32 v[124:125], 0
	v_mov_b64_e32 v[126:127], 0
	v_mov_b64_e32 v[128:129], 0
	s_cbranch_vccnz .LBB0_391
	s_branch .LBB0_392

; template <class Epi, class Sched, bool ALIGN_EPI = false, bool SP2 = false>
; __device__ __forceinline__ void gemm_phase(PG8_LAS unsigned char* lds, const Gemm g, const Sched& S, const Epi& E) {
;     ...
; #pragma unroll
;         for (int a = 0; a < 2; ++a)
; #pragma unroll
;             for (int b = 0; b < 2; ++b)
; #pragma unroll
;                 for (int m = 0; m < 4; ++m)
; #pragma unroll
;                     for (int n = 0; n < 2; ++n) acc[a][b][m][n] = (f32x4){0.f, 0.f, 0.f, 0.f};
;         cur = nxt; cA = nA; cB = nB; ++ui;
.LBB0_415:
	s_add_i32 s50, s63, -2
	s_add_u32 s18, s12, 0x80
	s_addc_u32 s19, s13, 0
	s_add_u32 s28, s28, 0x100
	s_addc_u32 s29, s29, 0
	s_mov_b32 s12, 0
	v_mov_b64_e32 v[2:3], 0
	v_mov_b64_e32 v[4:5], 0
	v_mov_b64_e32 v[6:7], 0
	v_mov_b64_e32 v[8:9], 0
	v_mov_b64_e32 v[10:11], 0
	v_mov_b64_e32 v[12:13], 0
	v_mov_b64_e32 v[14:15], 0
	v_mov_b64_e32 v[16:17], 0
	v_mov_b64_e32 v[18:19], 0
	v_mov_b64_e32 v[20:21], 0
	v_mov_b64_e32 v[22:23], 0
	v_mov_b64_e32 v[24:25], 0
	v_mov_b64_e32 v[26:27], 0
	v_mov_b64_e32 v[28:29], 0
	v_mov_b64_e32 v[30:31], 0
	v_mov_b64_e32 v[32:33], 0
	v_mov_b64_e32 v[34:35], 0
	v_mov_b64_e32 v[36:37], 0
	v_mov_b64_e32 v[38:39], 0
	v_mov_b64_e32 v[40:41], 0
	v_mov_b64_e32 v[42:43], 0
	v_mov_b64_e32 v[44:45], 0
	v_mov_b64_e32 v[46:47], 0
	v_mov_b64_e32 v[48:49], 0
	v_mov_b64_e32 v[50:51], 0
	v_mov_b64_e32 v[52:53], 0
	v_mov_b64_e32 v[54:55], 0
	v_mov_b64_e32 v[56:57], 0
	v_mov_b64_e32 v[58:59], 0
	v_mov_b64_e32 v[60:61], 0
	v_mov_b64_e32 v[62:63], 0
	v_mov_b64_e32 v[64:65], 0
	v_mov_b64_e32 v[66:67], 0
	v_mov_b64_e32 v[68:69], 0
	v_mov_b64_e32 v[70:71], 0
	v_mov_b64_e32 v[72:73], 0
	v_mov_b64_e32 v[74:75], 0
	v_mov_b64_e32 v[76:77], 0
	v_mov_b64_e32 v[78:79], 0
	v_mov_b64_e32 v[80:81], 0
	v_mov_b64_e32 v[82:83], 0
	v_mov_b64_e32 v[84:85], 0
	v_mov_b64_e32 v[86:87], 0
	v_mov_b64_e32 v[88:89], 0
	v_mov_b64_e32 v[90:91], 0
	v_mov_b64_e32 v[92:93], 0
	v_mov_b64_e32 v[94:95], 0
	v_mov_b64_e32 v[96:97], 0
	v_mov_b64_e32 v[98:99], 0
	v_mov_b64_e32 v[100:101], 0
	v_mov_b64_e32 v[102:103], 0
	v_mov_b64_e32 v[104:105], 0
	v_mov_b64_e32 v[106:107], 0
	v_mov_b64_e32 v[108:109], 0
	v_mov_b64_e32 v[110:111], 0
	v_mov_b64_e32 v[112:113], 0
	v_mov_b64_e32 v[114:115], 0
	v_mov_b64_e32 v[116:117], 0
	v_mov_b64_e32 v[118:119], 0
	v_mov_b64_e32 v[120:121], 0
	v_mov_b64_e32 v[122:123], 0
	v_mov_b64_e32 v[124:125], 0
	v_mov_b64_e32 v[126:127], 0
	v_mov_b64_e32 v[128:129], 0

; #define PG8_BAR __builtin_amdgcn_s_barrier()
; template <class Epi, class Sched, bool ALIGN_EPI = false, bool SP2 = false>
; __device__ __forceinline__ void gemm_phase(PG8_LAS unsigned char* lds, const Gemm g, const Sched& S, const Epi& E) {
;     ...
; #pragma unroll
;         for (int a = 0; a < 2; ++a)
; #pragma unroll
;             for (int b = 0; b < 2; ++b)
; #pragma unroll
;                 for (int m = 0; m < 4; ++m)
; #pragma unroll
;                     for (int n = 0; n < 2; ++n) acc[a][b][m][n] = (f32x4){0.f, 0.f, 0.f, 0.f};
;         cur = nxt; cA = nA; cB = nB; ++ui;
;         if constexpr (ALIGN_EPI) { if (wr == 1) PG8_BAR; }
.LBB0_424:
	s_and_b64 vcc, exec, s[30:31]
	v_mov_b64_e32 v[2:3], 0
	v_mov_b64_e32 v[4:5], 0
	v_mov_b64_e32 v[6:7], 0
	v_mov_b64_e32 v[8:9], 0
	v_mov_b64_e32 v[10:11], 0
	v_mov_b64_e32 v[12:13], 0
	v_mov_b64_e32 v[14:15], 0
	v_mov_b64_e32 v[16:17], 0
	v_mov_b64_e32 v[18:19], 0
	v_mov_b64_e32 v[20:21], 0
	v_mov_b64_e32 v[22:23], 0
	v_mov_b64_e32 v[24:25], 0
	v_mov_b64_e32 v[26:27], 0
	v_mov_b64_e32 v[28:29], 0
	v_mov_b64_e32 v[30:31], 0
	v_mov_b64_e32 v[32:33], 0
	v_mov_b64_e32 v[34:35], 0
	v_mov_b64_e32 v[36:37], 0
	v_mov_b64_e32 v[38:39], 0
	v_mov_b64_e32 v[40:41], 0
	v_mov_b64_e32 v[42:43], 0
	v_mov_b64_e32 v[44:45], 0
	v_mov_b64_e32 v[46:47], 0
	v_mov_b64_e32 v[48:49], 0
	v_mov_b64_e32 v[50:51], 0
	v_mov_b64_e32 v[52:53], 0
	v_mov_b64_e32 v[54:55], 0
	v_mov_b64_e32 v[56:57], 0
	v_mov_b64_e32 v[58:59], 0
	v_mov_b64_e32 v[60:61], 0
	v_mov_b64_e32 v[62:63], 0
	v_mov_b64_e32 v[64:65], 0
	v_mov_b64_e32 v[66:67], 0
	v_mov_b64_e32 v[68:69], 0
	v_mov_b64_e32 v[70:71], 0
	v_mov_b64_e32 v[72:73], 0
	v_mov_b64_e32 v[74:75], 0
	v_mov_b64_e32 v[76:77], 0
	v_mov_b64_e32 v[78:79], 0
	v_mov_b64_e32 v[80:81], 0
	v_mov_b64_e32 v[82:83], 0
	v_mov_b64_e32 v[84:85], 0
	v_mov_b64_e32 v[86:87], 0
	v_mov_b64_e32 v[88:89], 0
	v_mov_b64_e32 v[90:91], 0
	v_mov_b64_e32 v[92:93], 0
	v_mov_b64_e32 v[94:95], 0
	v_mov_b64_e32 v[96:97], 0
	v_mov_b64_e32 v[98:99], 0
	v_mov_b64_e32 v[100:101], 0
	v_mov_b64_e32 v[102:103], 0
	v_mov_b64_e32 v[104:105], 0
	v_mov_b64_e32 v[106:107], 0
	v_mov_b64_e32 v[108:109], 0
	v_mov_b64_e32 v[110:111], 0
	v_mov_b64_e32 v[112:113], 0
	v_mov_b64_e32 v[114:115], 0
	v_mov_b64_e32 v[116:117], 0
	v_mov_b64_e32 v[118:119], 0
	v_mov_b64_e32 v[120:121], 0
	v_mov_b64_e32 v[122:123], 0
	v_mov_b64_e32 v[124:125], 0
	v_mov_b64_e32 v[126:127], 0
	v_mov_b64_e32 v[128:129], 0
	s_cbranch_vccnz .LBB0_418
	s_branch .LBB0_419

; template <class Epi, class Sched, bool ALIGN_EPI = false, bool SP2 = false>
; __device__ __forceinline__ void gemm_phase(PG8_LAS unsigned char* lds, const Gemm g, const Sched& S, const Epi& E) {
;     ...
; #pragma unroll
;         for (int a = 0; a < 2; ++a)
; #pragma unroll
;             for (int b = 0; b < 2; ++b)
; #pragma unroll
;                 for (int m = 0; m < 4; ++m)
; #pragma unroll
;                     for (int n = 0; n < 2; ++n) acc[a][b][m][n] = (f32x4){0.f, 0.f, 0.f, 0.f};
;         cur = nxt; cA = nA; cB = nB; ++ui;
.LBB0_455:
	s_add_i32 s19, s48, -2
	s_add_u32 s44, s44, 0x80
	s_addc_u32 s45, s45, 0
	s_add_u32 s69, s12, 0x100
	s_addc_u32 s72, s13, 0
	s_mov_b32 s12, 0
	v_mov_b64_e32 v[2:3], 0
	v_mov_b64_e32 v[4:5], 0
	v_mov_b64_e32 v[6:7], 0
	v_mov_b64_e32 v[8:9], 0
	v_mov_b64_e32 v[10:11], 0
	v_mov_b64_e32 v[12:13], 0
	v_mov_b64_e32 v[14:15], 0
	v_mov_b64_e32 v[16:17], 0
	v_mov_b64_e32 v[18:19], 0
	v_mov_b64_e32 v[20:21], 0
	v_mov_b64_e32 v[22:23], 0
	v_mov_b64_e32 v[24:25], 0
	v_mov_b64_e32 v[26:27], 0
	v_mov_b64_e32 v[28:29], 0
	v_mov_b64_e32 v[30:31], 0
	v_mov_b64_e32 v[32:33], 0
	v_mov_b64_e32 v[34:35], 0
	v_mov_b64_e32 v[36:37], 0
	v_mov_b64_e32 v[38:39], 0
	v_mov_b64_e32 v[40:41], 0
	v_mov_b64_e32 v[42:43], 0
	v_mov_b64_e32 v[44:45], 0
	v_mov_b64_e32 v[46:47], 0
	v_mov_b64_e32 v[48:49], 0
	v_mov_b64_e32 v[50:51], 0
	v_mov_b64_e32 v[52:53], 0
	v_mov_b64_e32 v[54:55], 0
	v_mov_b64_e32 v[56:57], 0
	v_mov_b64_e32 v[58:59], 0
	v_mov_b64_e32 v[60:61], 0
	v_mov_b64_e32 v[62:63], 0
	v_mov_b64_e32 v[64:65], 0
	v_mov_b64_e32 v[66:67], 0
	v_mov_b64_e32 v[68:69], 0
	v_mov_b64_e32 v[70:71], 0
	v_mov_b64_e32 v[72:73], 0
	v_mov_b64_e32 v[74:75], 0
	v_mov_b64_e32 v[76:77], 0
	v_mov_b64_e32 v[78:79], 0
	v_mov_b64_e32 v[80:81], 0
	v_mov_b64_e32 v[82:83], 0
	v_mov_b64_e32 v[84:85], 0
	v_mov_b64_e32 v[86:87], 0
	v_mov_b64_e32 v[88:89], 0
	v_mov_b64_e32 v[90:91], 0
	v_mov_b64_e32 v[92:93], 0
	v_mov_b64_e32 v[94:95], 0
	v_mov_b64_e32 v[96:97], 0
	v_mov_b64_e32 v[98:99], 0
	v_mov_b64_e32 v[100:101], 0
	v_mov_b64_e32 v[102:103], 0
	v_mov_b64_e32 v[104:105], 0
	v_mov_b64_e32 v[106:107], 0
	v_mov_b64_e32 v[108:109], 0
	v_mov_b64_e32 v[110:111], 0
	v_mov_b64_e32 v[112:113], 0
	v_mov_b64_e32 v[114:115], 0
	v_mov_b64_e32 v[116:117], 0
	v_mov_b64_e32 v[118:119], 0
	v_mov_b64_e32 v[120:121], 0
	v_mov_b64_e32 v[122:123], 0
	v_mov_b64_e32 v[124:125], 0
	v_mov_b64_e32 v[126:127], 0
	v_mov_b64_e32 v[128:129], 0

; template <class Epi, class Sched, bool ALIGN_EPI = false, bool SP2 = false>
; __device__ __forceinline__ void gemm_phase(PG8_LAS unsigned char* lds, const Gemm g, const Sched& S, const Epi& E) {
;     ...
; #pragma unroll
;         for (int a = 0; a < 2; ++a)
; #pragma unroll
;             for (int b = 0; b < 2; ++b)
; #pragma unroll
;                 for (int m = 0; m < 4; ++m)
; #pragma unroll
;                     for (int n = 0; n < 2; ++n) acc[a][b][m][n] = (f32x4){0.f, 0.f, 0.f, 0.f};
.LBB0_460:
	v_mov_b64_e32 v[2:3], 0
	v_mov_b64_e32 v[4:5], 0
	v_mov_b64_e32 v[6:7], 0
	v_mov_b64_e32 v[8:9], 0
	v_mov_b64_e32 v[10:11], 0
	v_mov_b64_e32 v[12:13], 0
	v_mov_b64_e32 v[14:15], 0
	v_mov_b64_e32 v[16:17], 0
	v_mov_b64_e32 v[18:19], 0
	v_mov_b64_e32 v[20:21], 0
	v_mov_b64_e32 v[22:23], 0
	v_mov_b64_e32 v[24:25], 0
	v_mov_b64_e32 v[26:27], 0
	v_mov_b64_e32 v[28:29], 0
	v_mov_b64_e32 v[30:31], 0
	v_mov_b64_e32 v[32:33], 0
	v_mov_b64_e32 v[34:35], 0
	v_mov_b64_e32 v[36:37], 0
	v_mov_b64_e32 v[38:39], 0
	v_mov_b64_e32 v[40:41], 0
	v_mov_b64_e32 v[42:43], 0
	v_mov_b64_e32 v[44:45], 0
	v_mov_b64_e32 v[46:47], 0
	v_mov_b64_e32 v[48:49], 0
	v_mov_b64_e32 v[50:51], 0
	v_mov_b64_e32 v[52:53], 0
	v_mov_b64_e32 v[54:55], 0
	v_mov_b64_e32 v[56:57], 0
	v_mov_b64_e32 v[58:59], 0
	v_mov_b64_e32 v[60:61], 0
	v_mov_b64_e32 v[62:63], 0
	v_mov_b64_e32 v[64:65], 0
	v_mov_b64_e32 v[66:67], 0
	v_mov_b64_e32 v[68:69], 0
	v_mov_b64_e32 v[70:71], 0
	v_mov_b64_e32 v[72:73], 0
	v_mov_b64_e32 v[74:75], 0
	v_mov_b64_e32 v[76:77], 0
	v_mov_b64_e32 v[78:79], 0
	v_mov_b64_e32 v[80:81], 0
	v_mov_b64_e32 v[82:83], 0
	v_mov_b64_e32 v[84:85], 0
	v_mov_b64_e32 v[86:87], 0
	v_mov_b64_e32 v[88:89], 0
	v_mov_b64_e32 v[90:91], 0
	v_mov_b64_e32 v[92:93], 0
	v_mov_b64_e32 v[94:95], 0
	v_mov_b64_e32 v[96:97], 0
	v_mov_b64_e32 v[98:99], 0
	v_mov_b64_e32 v[100:101], 0
	v_mov_b64_e32 v[102:103], 0
	v_mov_b64_e32 v[104:105], 0
	v_mov_b64_e32 v[106:107], 0
	v_mov_b64_e32 v[108:109], 0
	v_mov_b64_e32 v[110:111], 0
	v_mov_b64_e32 v[112:113], 0
	v_mov_b64_e32 v[114:115], 0
	v_mov_b64_e32 v[116:117], 0
	v_mov_b64_e32 v[118:119], 0
	v_mov_b64_e32 v[120:121], 0
	v_mov_b64_e32 v[122:123], 0
	v_mov_b64_e32 v[124:125], 0
	v_mov_b64_e32 v[126:127], 0
	v_mov_b64_e32 v[128:129], 0
